# v12_nohoist
# speedup vs baseline: 1.0074x; 1.0074x over previous
; __device__ __forceinline__ void gemm_tile(const Params& P, const GArgs& ga, const TileDesc& td, int wid_s) {
;     ...
;   const int ewr = tid2_ >> 8, ewc = (tid2_ >> 6) & 3, efr = tid2_ & 15, efq = (tid2_ >> 4) & 3;
;   const int rbase = brow + ewr * 64 + efq * 4;
;   const int x4 = (ewc * 16 + efr) * 4;
;   const int c4 = bcol + x4;
;     ...
;   } else if (mode == M_PART) {
;     u16* __restrict__ pp = WSU(PART) + ((size_t)sp * NS + (rbase - NP)) * DM + c4;
;     static_for<32>([&](auto ic) __attribute__((always_inline)) {
;       EPI_IDX;
;       uint2 o; o.x = pack2(acc[ai][0][m][0][j], acc[ai][0][m][1][j]); o.y = pack2(acc[ai][1][m][0][j], acc[ai][1][m][1][j]);
;       *reinterpret_cast<uint2*>(pp + (size_t)rl * DM) = o;
;       if constexpr ((idx & 7) == 7) __builtin_amdgcn_sched_barrier(0);
;     });
.LBB0_313:
	s_or_b64 exec, exec, s[0:1]
	s_mov_b32 s17, 0x358637bd
	v_mov_b32_e32 v0, v200
	s_mov_b64 s[0:1], -1
	v_ashrrev_i32_e32 v130, 2, v0
	v_and_b32_e32 v203, 15, v0
	v_and_b32_e32 v130, 0xffffffc0, v130
	v_lshrrev_b32_e32 v131, 2, v0
	v_and_b32_e32 v0, 0xc0, v0
	v_add_u32_e32 v130, s84, v130
	v_lshl_or_b32 v0, v203, 2, v0
	v_and_or_b32 v166, v131, 12, v130
	v_or_b32_e32 v168, s92, v0
	s_mov_b64 s[84:85], 0
	s_cmp_lt_i32 s79, 2
	s_mov_b64 s[8:9], 0
	s_cbranch_scc1 .LBB0_597
	s_cmp_gt_i32 s79, 2
	s_cbranch_scc0 .LBB0_323
	s_cmp_gt_i32 s79, 4
	s_cbranch_scc0 .LBB0_319
	s_cmp_eq_u32 s79, 5
	s_mov_b64 s[8:9], -1
	s_cbranch_scc0 .LBB0_318
	s_lshl_b32 s0, s87, 22
	v_readlane_b32 s4, v231, 62
	v_ashrrev_i32_e32 v167, 31, v166
	v_readlane_b32 s5, v231, 63
	s_add_u32 s0, s4, s0
	v_lshlrev_b64 v[130:131], 12, v[166:167]
	s_addc_u32 s1, s5, 0
	v_lshl_add_u64 v[130:131], s[0:1], 0, v[130:131]
	v_ashrrev_i32_e32 v169, 31, v168
	v_lshl_add_u64 v[130:131], v[168:169], 1, v[130:131]
	s_mov_b32 s0, 0xfc001000
	v_add_co_u32_e32 v134, vcc, s0, v130
	v_cvt_pk_bf16_f32 v132, v114, v118
	v_cvt_pk_bf16_f32 v133, v126, v122
	v_addc_co_u32_e32 v135, vcc, -1, v131, vcc
	global_store_dwordx2 v[134:135], v[132:133], off offset:-4096 nt
	v_cvt_pk_bf16_f32 v132, v115, v119
	v_cvt_pk_bf16_f32 v133, v127, v123
	s_mov_b32 s0, 0xfc003000
	global_store_dwordx2 v[134:135], v[132:133], off nt
	v_add_co_u32_e32 v134, vcc, s0, v130
	v_cvt_pk_bf16_f32 v132, v116, v120
	v_cvt_pk_bf16_f32 v133, v128, v124
	v_addc_co_u32_e32 v135, vcc, -1, v131, vcc
	global_store_dwordx2 v[134:135], v[132:133], off offset:-4096 nt
	v_cvt_pk_bf16_f32 v132, v117, v121
	v_cvt_pk_bf16_f32 v133, v129, v125
	s_mov_b32 s0, 0xfc011000
	global_store_dwordx2 v[134:135], v[132:133], off nt
	v_add_co_u32_e32 v134, vcc, s0, v130
	v_cvt_pk_bf16_f32 v132, v98, v102
	v_cvt_pk_bf16_f32 v133, v110, v106
	v_addc_co_u32_e32 v135, vcc, -1, v131, vcc
	global_store_dwordx2 v[134:135], v[132:133], off offset:-4096 nt
	v_cvt_pk_bf16_f32 v132, v99, v103
	v_cvt_pk_bf16_f32 v133, v111, v107
	s_mov_b32 s0, 0xfc013000
	global_store_dwordx2 v[134:135], v[132:133], off nt
	v_add_co_u32_e32 v134, vcc, s0, v130
	v_cvt_pk_bf16_f32 v132, v100, v104
	v_cvt_pk_bf16_f32 v133, v112, v108
	v_addc_co_u32_e32 v135, vcc, -1, v131, vcc
	global_store_dwordx2 v[134:135], v[132:133], off offset:-4096 nt
	v_cvt_pk_bf16_f32 v132, v101, v105
	v_cvt_pk_bf16_f32 v133, v113, v109
	global_store_dwordx2 v[134:135], v[132:133], off nt
	s_mov_b32 s0, 0xfc021000
	v_add_co_u32_e32 v134, vcc, s0, v130
	v_cvt_pk_bf16_f32 v132, v82, v86
	v_cvt_pk_bf16_f32 v133, v94, v90
	v_addc_co_u32_e32 v135, vcc, -1, v131, vcc
	global_store_dwordx2 v[134:135], v[132:133], off offset:-4096 nt
	v_cvt_pk_bf16_f32 v132, v83, v87
	v_cvt_pk_bf16_f32 v133, v95, v91
	s_mov_b32 s0, 0xfc023000
	global_store_dwordx2 v[134:135], v[132:133], off nt
	v_add_co_u32_e32 v134, vcc, s0, v130
	v_cvt_pk_bf16_f32 v132, v84, v88
	v_cvt_pk_bf16_f32 v133, v96, v92
	v_addc_co_u32_e32 v135, vcc, -1, v131, vcc
	global_store_dwordx2 v[134:135], v[132:133], off offset:-4096 nt
	v_cvt_pk_bf16_f32 v132, v85, v89
	v_cvt_pk_bf16_f32 v133, v97, v93
	s_mov_b32 s0, 0xfc031000
	global_store_dwordx2 v[134:135], v[132:133], off nt
	v_add_co_u32_e32 v134, vcc, s0, v130
	v_cvt_pk_bf16_f32 v132, v66, v70
	v_cvt_pk_bf16_f32 v133, v78, v74
	v_addc_co_u32_e32 v135, vcc, -1, v131, vcc
	global_store_dwordx2 v[134:135], v[132:133], off offset:-4096 nt
	v_cvt_pk_bf16_f32 v132, v67, v71
	v_cvt_pk_bf16_f32 v133, v79, v75
	s_mov_b32 s0, 0xfc033000
	global_store_dwordx2 v[134:135], v[132:133], off nt
	v_add_co_u32_e32 v134, vcc, s0, v130
	v_cvt_pk_bf16_f32 v132, v68, v72
	v_cvt_pk_bf16_f32 v133, v80, v76
	v_addc_co_u32_e32 v135, vcc, -1, v131, vcc
	global_store_dwordx2 v[134:135], v[132:133], off offset:-4096 nt
	v_cvt_pk_bf16_f32 v132, v69, v73
	v_cvt_pk_bf16_f32 v133, v81, v77
	global_store_dwordx2 v[134:135], v[132:133], off nt
	s_mov_b32 s0, 0xfc081000
	v_add_co_u32_e32 v134, vcc, s0, v130
	v_cvt_pk_bf16_f32 v132, v50, v54
	v_cvt_pk_bf16_f32 v133, v62, v58
	v_addc_co_u32_e32 v135, vcc, -1, v131, vcc
	global_store_dwordx2 v[134:135], v[132:133], off offset:-4096 nt
	v_cvt_pk_bf16_f32 v132, v51, v55
	v_cvt_pk_bf16_f32 v133, v63, v59
	s_mov_b32 s0, 0xfc083000
	global_store_dwordx2 v[134:135], v[132:133], off nt
	v_add_co_u32_e32 v134, vcc, s0, v130
	v_cvt_pk_bf16_f32 v132, v52, v56
	v_cvt_pk_bf16_f32 v133, v64, v60
	v_addc_co_u32_e32 v135, vcc, -1, v131, vcc
	global_store_dwordx2 v[134:135], v[132:133], off offset:-4096 nt
	v_cvt_pk_bf16_f32 v132, v53, v57
	v_cvt_pk_bf16_f32 v133, v65, v61
	s_mov_b32 s0, 0xfc091000
	global_store_dwordx2 v[134:135], v[132:133], off nt
	v_add_co_u32_e32 v134, vcc, s0, v130
	v_cvt_pk_bf16_f32 v132, v34, v38
	v_cvt_pk_bf16_f32 v133, v46, v42
	v_addc_co_u32_e32 v135, vcc, -1, v131, vcc
	global_store_dwordx2 v[134:135], v[132:133], off offset:-4096 nt
	v_cvt_pk_bf16_f32 v132, v35, v39
	v_cvt_pk_bf16_f32 v133, v47, v43
	s_mov_b32 s0, 0xfc093000
	global_store_dwordx2 v[134:135], v[132:133], off nt
	v_add_co_u32_e32 v134, vcc, s0, v130
	v_cvt_pk_bf16_f32 v132, v36, v40
	v_cvt_pk_bf16_f32 v133, v48, v44
	v_addc_co_u32_e32 v135, vcc, -1, v131, vcc
	global_store_dwordx2 v[134:135], v[132:133], off offset:-4096 nt
	v_cvt_pk_bf16_f32 v132, v37, v41
	v_cvt_pk_bf16_f32 v133, v49, v45
	global_store_dwordx2 v[134:135], v[132:133], off nt
	s_mov_b32 s0, 0xfc0a1000
	v_add_co_u32_e32 v134, vcc, s0, v130
	v_cvt_pk_bf16_f32 v132, v18, v22
	v_cvt_pk_bf16_f32 v133, v30, v26
	v_addc_co_u32_e32 v135, vcc, -1, v131, vcc
	global_store_dwordx2 v[134:135], v[132:133], off offset:-4096 nt
	v_cvt_pk_bf16_f32 v132, v19, v23
	v_cvt_pk_bf16_f32 v133, v31, v27
	s_mov_b32 s0, 0xfc0a3000
	global_store_dwordx2 v[134:135], v[132:133], off nt
	v_add_co_u32_e32 v134, vcc, s0, v130
	v_cvt_pk_bf16_f32 v132, v20, v24
	v_cvt_pk_bf16_f32 v133, v32, v28
	v_addc_co_u32_e32 v135, vcc, -1, v131, vcc
	global_store_dwordx2 v[134:135], v[132:133], off offset:-4096 nt
	v_cvt_pk_bf16_f32 v132, v21, v25
	v_cvt_pk_bf16_f32 v133, v33, v29
	s_mov_b32 s0, 0xfc0b1000
	global_store_dwordx2 v[134:135], v[132:133], off nt
	v_add_co_u32_e32 v134, vcc, s0, v130
	v_cvt_pk_bf16_f32 v132, v2, v6
	v_cvt_pk_bf16_f32 v133, v14, v10
	v_addc_co_u32_e32 v135, vcc, -1, v131, vcc
	global_store_dwordx2 v[134:135], v[132:133], off offset:-4096 nt
	v_cvt_pk_bf16_f32 v132, v3, v7
	v_cvt_pk_bf16_f32 v133, v15, v11
	s_mov_b32 s0, 0xfc0b2000
	global_store_dwordx2 v[134:135], v[132:133], off nt
	v_add_co_u32_e32 v134, vcc, s0, v130
	v_cvt_pk_bf16_f32 v132, v4, v8
	s_nop 0
	v_addc_co_u32_e32 v135, vcc, -1, v131, vcc
	v_cvt_pk_bf16_f32 v133, v16, v12
	v_add_co_u32_e32 v130, vcc, 0xfc0b3000, v130
	global_store_dwordx2 v[134:135], v[132:133], off nt
	v_cvt_pk_bf16_f32 v132, v5, v9
	v_cvt_pk_bf16_f32 v133, v17, v13
	v_addc_co_u32_e32 v131, vcc, -1, v131, vcc
	global_store_dwordx2 v[130:131], v[132:133], off nt
	s_mov_b64 s[8:9], 0

; __device__ __forceinline__ float fdiv(float a, float b) { return a * __builtin_amdgcn_rcpf(b); }
; __device__ __forceinline__ void gemm_tile(const Params& P, const GArgs& ga, const TileDesc& td, int wid_s) {
;     ...
;   if (mode == M_GU) {
;     LOAD_RSV
;     unsigned* __restrict__ G = reinterpret_cast<unsigned*>(WSU(G) + (size_t)rbase * FF + (bcol >> 1) + (x4 >> 1));
;     static_for<32>([&](auto ic) __attribute__((always_inline)) {
;       EPI_IDX;
;       const float rs = rsv[idx];
;       float g0 = rs * acc[ai][0][m][0][j], u0 = rs * acc[ai][0][m][1][j];
;       float g1 = rs * acc[ai][1][m][0][j], u1 = rs * acc[ai][1][m][1][j];
;       __builtin_nontemporal_store(pack2(fdiv(g0 * u0, 1.f + __expf(-g0)), fdiv(g1 * u1, 1.f + __expf(-g1))), G + (size_t)rl * (FF / 2));
;       if constexpr ((idx & 7) == 7) __builtin_amdgcn_sched_barrier(0);
;     });
.LBB0_748:
	s_and_b64 vcc, exec, s[84:85]
	s_cbranch_vccz .LBB0_290
	v_lshl_add_u64 v[194:195], v[166:167], 2, s[72:73]
	global_load_dwordx4 v[130:133], v[194:195], off
	global_load_dwordx4 v[134:137], v[194:195], off offset:64
	global_load_dwordx4 v[138:141], v[194:195], off offset:128
	global_load_dwordx4 v[142:145], v[194:195], off offset:192
	global_load_dwordx4 v[146:149], v[194:195], off offset:512
	global_load_dwordx4 v[150:153], v[194:195], off offset:576
	global_load_dwordx4 v[154:157], v[194:195], off offset:640
	global_load_dwordx4 v[158:161], v[194:195], off offset:704
	v_and_b32_e32 v196, 15, v200
	v_and_b32_e32 v197, 0xc0, v200
	v_lshl_or_b32 v196, v196, 2, v197
	s_lshl_b32 s0, s15, 8
	v_mov_b32_e32 v197, 0x2c00
	v_mad_u32_u24 v196, v166, v197, v196
	v_mov_b32_e32 v198, s17
	v_add_u32_e32 v196, s0, v196
	s_waitcnt vmcnt(7)
	v_fmamk_f32 v130, v130, 0x3a000000, v198
	v_fmamk_f32 v131, v131, 0x3a000000, v198
	v_fmamk_f32 v132, v132, 0x3a000000, v198
	v_fmamk_f32 v133, v133, 0x3a000000, v198
	v_rsq_f32_e32 v162, v130
	v_rsq_f32_e32 v163, v131
	v_rsq_f32_e32 v164, v132
	v_rsq_f32_e32 v165, v133
	s_waitcnt vmcnt(6)
	v_fmamk_f32 v134, v134, 0x3a000000, v198
	v_fmamk_f32 v135, v135, 0x3a000000, v198
	v_fmamk_f32 v136, v136, 0x3a000000, v198
	v_fmamk_f32 v137, v137, 0x3a000000, v198
	v_rsq_f32_e32 v166, v134
	v_rsq_f32_e32 v167, v135
	v_rsq_f32_e32 v168, v136
	v_rsq_f32_e32 v169, v137
	v_mul_f32_e32 v162, 0xbfb8aa3b, v162
	v_mul_f32_e32 v163, 0xbfb8aa3b, v163
	v_mul_f32_e32 v164, 0xbfb8aa3b, v164
	v_mul_f32_e32 v165, 0xbfb8aa3b, v165
	s_waitcnt vmcnt(5)
	v_fmamk_f32 v138, v138, 0x3a000000, v198
	v_fmamk_f32 v139, v139, 0x3a000000, v198
	v_fmamk_f32 v140, v140, 0x3a000000, v198
	v_fmamk_f32 v141, v141, 0x3a000000, v198
	v_rsq_f32_e32 v170, v138
	v_rsq_f32_e32 v171, v139
	v_rsq_f32_e32 v172, v140
	v_rsq_f32_e32 v173, v141
	v_mul_f32_e32 v166, 0xbfb8aa3b, v166
	v_mul_f32_e32 v167, 0xbfb8aa3b, v167
	v_mul_f32_e32 v168, 0xbfb8aa3b, v168
	v_mul_f32_e32 v169, 0xbfb8aa3b, v169
	s_waitcnt vmcnt(4)
	v_fmamk_f32 v142, v142, 0x3a000000, v198
	v_fmamk_f32 v143, v143, 0x3a000000, v198
	v_fmamk_f32 v144, v144, 0x3a000000, v198
	v_fmamk_f32 v145, v145, 0x3a000000, v198
	v_rsq_f32_e32 v174, v142
	v_rsq_f32_e32 v175, v143
	v_rsq_f32_e32 v176, v144
	v_rsq_f32_e32 v177, v145
	v_mul_f32_e32 v170, 0xbfb8aa3b, v170
	v_mul_f32_e32 v171, 0xbfb8aa3b, v171
	v_mul_f32_e32 v172, 0xbfb8aa3b, v172
	v_mul_f32_e32 v173, 0xbfb8aa3b, v173
	s_waitcnt vmcnt(3)
	v_fmamk_f32 v146, v146, 0x3a000000, v198
	v_fmamk_f32 v147, v147, 0x3a000000, v198
	v_fmamk_f32 v148, v148, 0x3a000000, v198
	v_fmamk_f32 v149, v149, 0x3a000000, v198
	v_rsq_f32_e32 v178, v146
	v_rsq_f32_e32 v179, v147
	v_rsq_f32_e32 v180, v148
	v_rsq_f32_e32 v181, v149
	v_mul_f32_e32 v174, 0xbfb8aa3b, v174
	v_mul_f32_e32 v175, 0xbfb8aa3b, v175
	v_mul_f32_e32 v176, 0xbfb8aa3b, v176
	v_mul_f32_e32 v177, 0xbfb8aa3b, v177
	s_waitcnt vmcnt(2)
	v_fmamk_f32 v150, v150, 0x3a000000, v198
	v_fmamk_f32 v151, v151, 0x3a000000, v198
	v_fmamk_f32 v152, v152, 0x3a000000, v198
	v_fmamk_f32 v153, v153, 0x3a000000, v198
	v_rsq_f32_e32 v182, v150
	v_rsq_f32_e32 v183, v151
	v_rsq_f32_e32 v184, v152
	v_rsq_f32_e32 v185, v153
	v_mul_f32_e32 v178, 0xbfb8aa3b, v178
	v_mul_f32_e32 v179, 0xbfb8aa3b, v179
	v_mul_f32_e32 v180, 0xbfb8aa3b, v180
	v_mul_f32_e32 v181, 0xbfb8aa3b, v181
	s_waitcnt vmcnt(1)
	v_fmamk_f32 v154, v154, 0x3a000000, v198
	v_fmamk_f32 v155, v155, 0x3a000000, v198
	v_fmamk_f32 v156, v156, 0x3a000000, v198
	v_fmamk_f32 v157, v157, 0x3a000000, v198
	v_rsq_f32_e32 v186, v154
	v_rsq_f32_e32 v187, v155
	v_rsq_f32_e32 v188, v156
	v_rsq_f32_e32 v189, v157
	v_mul_f32_e32 v182, 0xbfb8aa3b, v182
	v_mul_f32_e32 v183, 0xbfb8aa3b, v183
	v_mul_f32_e32 v184, 0xbfb8aa3b, v184
	v_mul_f32_e32 v185, 0xbfb8aa3b, v185
	s_waitcnt vmcnt(0)
	v_fmamk_f32 v158, v158, 0x3a000000, v198
	v_fmamk_f32 v159, v159, 0x3a000000, v198
	v_fmamk_f32 v160, v160, 0x3a000000, v198
	v_fmamk_f32 v161, v161, 0x3a000000, v198
	v_rsq_f32_e32 v190, v158
	v_rsq_f32_e32 v191, v159
	v_rsq_f32_e32 v192, v160
	v_rsq_f32_e32 v193, v161
	v_mul_f32_e32 v186, 0xbfb8aa3b, v186
	v_mul_f32_e32 v187, 0xbfb8aa3b, v187
	v_mul_f32_e32 v188, 0xbfb8aa3b, v188
	v_mul_f32_e32 v189, 0xbfb8aa3b, v189
	s_nop 0
	v_mul_f32_e32 v190, 0xbfb8aa3b, v190
	v_mul_f32_e32 v191, 0xbfb8aa3b, v191
	v_mul_f32_e32 v192, 0xbfb8aa3b, v192
	v_mul_f32_e32 v193, 0xbfb8aa3b, v193
	v_mul_f32_e32 v204, v114, v162
	v_mul_f32_e32 v205, v126, v162
	v_mul_f32_e32 v206, v115, v163
	v_mul_f32_e32 v207, v127, v163
	v_mul_f32_e32 v208, v116, v164
	v_mul_f32_e32 v209, v128, v164
	v_mul_f32_e32 v210, v117, v165
	v_mul_f32_e32 v211, v129, v165
	v_exp_f32_e32 v204, v204
	v_exp_f32_e32 v205, v205
	v_exp_f32_e32 v206, v206
	v_exp_f32_e32 v207, v207
	v_exp_f32_e32 v208, v208
	v_exp_f32_e32 v209, v209
	v_exp_f32_e32 v210, v210
	v_exp_f32_e32 v211, v211
	v_mul_f32_e32 v212, v114, v118
	v_mul_f32_e32 v213, v126, v122
	v_mul_f32_e32 v214, v115, v119
	v_mul_f32_e32 v215, v127, v123
	v_mul_f32_e32 v216, v116, v120
	v_mul_f32_e32 v217, v128, v124
	v_mul_f32_e32 v218, v117, v121
	v_mul_f32_e32 v219, v129, v125
	v_fma_f32 v204, v204, v130, v130
	v_fma_f32 v205, v205, v130, v130
	v_fma_f32 v206, v206, v131, v131
	v_fma_f32 v207, v207, v131, v131
	v_fma_f32 v208, v208, v132, v132
	v_fma_f32 v209, v209, v132, v132
	v_fma_f32 v210, v210, v133, v133
	v_fma_f32 v211, v211, v133, v133
	v_rcp_f32_e32 v204, v204
	v_rcp_f32_e32 v205, v205
	v_rcp_f32_e32 v206, v206
	v_rcp_f32_e32 v207, v207
	v_rcp_f32_e32 v208, v208
	v_rcp_f32_e32 v209, v209
	v_rcp_f32_e32 v210, v210
	v_rcp_f32_e32 v211, v211
	v_mul_f32_e32 v212, v212, v204
	v_mul_f32_e32 v213, v213, v205
; __device__ __forceinline__ float fdiv(float a, float b) { return a * __builtin_amdgcn_rcpf(b); }
; __device__ __forceinline__ void gemm_tile(const Params& P, const GArgs& ga, const TileDesc& td, int wid_s) {
;     ...
;     unsigned* __restrict__ G = reinterpret_cast<unsigned*>(WSU(G) + (size_t)rbase * FF + (bcol >> 1) + (x4 >> 1));
;     static_for<32>([&](auto ic) __attribute__((always_inline)) {
;       EPI_IDX;
;       const float rs = rsv[idx];
;       float g0 = rs * acc[ai][0][m][0][j], u0 = rs * acc[ai][0][m][1][j];
;       float g1 = rs * acc[ai][1][m][0][j], u1 = rs * acc[ai][1][m][1][j];
;       __builtin_nontemporal_store(pack2(fdiv(g0 * u0, 1.f + __expf(-g0)), fdiv(g1 * u1, 1.f + __expf(-g1))), G + (size_t)rl * (FF / 2));
;       if constexpr ((idx & 7) == 7) __builtin_amdgcn_sched_barrier(0);
;     });
	v_mul_f32_e32 v214, v214, v206
	v_mul_f32_e32 v215, v215, v207
	s_add_u32 s4, s24, 0x0
	s_addc_u32 s5, s25, 0
	v_mul_f32_e32 v216, v216, v208
	v_mul_f32_e32 v217, v217, v209
	v_mul_f32_e32 v218, v218, v210
	v_mul_f32_e32 v219, v219, v211
	v_cvt_pk_bf16_f32 v220, v212, v213
	v_cvt_pk_bf16_f32 v221, v214, v215
	v_cvt_pk_bf16_f32 v222, v216, v217
	v_cvt_pk_bf16_f32 v223, v218, v219
	global_store_dword v196, v220, s[4:5]
	s_add_u32 s4, s4, 0x2c00
	s_addc_u32 s5, s5, 0
	global_store_dword v196, v221, s[4:5]
	s_add_u32 s4, s4, 0x2c00
	s_addc_u32 s5, s5, 0
	global_store_dword v196, v222, s[4:5]
	s_add_u32 s4, s4, 0x2c00
	s_addc_u32 s5, s5, 0
	global_store_dword v196, v223, s[4:5]
	v_mul_f32_e32 v204, v98, v166
	v_mul_f32_e32 v205, v110, v166
	v_mul_f32_e32 v206, v99, v167
	v_mul_f32_e32 v207, v111, v167
	v_mul_f32_e32 v208, v100, v168
	v_mul_f32_e32 v209, v112, v168
	v_mul_f32_e32 v210, v101, v169
	v_mul_f32_e32 v211, v113, v169
	v_exp_f32_e32 v204, v204
	v_exp_f32_e32 v205, v205
	v_exp_f32_e32 v206, v206
	v_exp_f32_e32 v207, v207
	v_exp_f32_e32 v208, v208
	v_exp_f32_e32 v209, v209
	v_exp_f32_e32 v210, v210
	v_exp_f32_e32 v211, v211
	v_mul_f32_e32 v212, v98, v102
	v_mul_f32_e32 v213, v110, v106
	v_mul_f32_e32 v214, v99, v103
	v_mul_f32_e32 v215, v111, v107
	v_mul_f32_e32 v216, v100, v104
	v_mul_f32_e32 v217, v112, v108
	v_mul_f32_e32 v218, v101, v105
	v_mul_f32_e32 v219, v113, v109
	v_fma_f32 v204, v204, v134, v134
	v_fma_f32 v205, v205, v134, v134
	v_fma_f32 v206, v206, v135, v135
	v_fma_f32 v207, v207, v135, v135
	v_fma_f32 v208, v208, v136, v136
	v_fma_f32 v209, v209, v136, v136
	v_fma_f32 v210, v210, v137, v137
	v_fma_f32 v211, v211, v137, v137
	v_rcp_f32_e32 v204, v204
	v_rcp_f32_e32 v205, v205
	v_rcp_f32_e32 v206, v206
	v_rcp_f32_e32 v207, v207
	v_rcp_f32_e32 v208, v208
	v_rcp_f32_e32 v209, v209
	v_rcp_f32_e32 v210, v210
	v_rcp_f32_e32 v211, v211
	v_mul_f32_e32 v212, v212, v204
	v_mul_f32_e32 v213, v213, v205
	v_mul_f32_e32 v214, v214, v206
	v_mul_f32_e32 v215, v215, v207
	s_add_u32 s4, s24, 0x2c000
	s_addc_u32 s5, s25, 0
	v_mul_f32_e32 v216, v216, v208
	v_mul_f32_e32 v217, v217, v209
	v_mul_f32_e32 v218, v218, v210
	v_mul_f32_e32 v219, v219, v211
	v_cvt_pk_bf16_f32 v220, v212, v213
	v_cvt_pk_bf16_f32 v221, v214, v215
	v_cvt_pk_bf16_f32 v222, v216, v217
	v_cvt_pk_bf16_f32 v223, v218, v219
	global_store_dword v196, v220, s[4:5]
	s_add_u32 s4, s4, 0x2c00
	s_addc_u32 s5, s5, 0
	global_store_dword v196, v221, s[4:5]
	s_add_u32 s4, s4, 0x2c00
	s_addc_u32 s5, s5, 0
	global_store_dword v196, v222, s[4:5]
	s_add_u32 s4, s4, 0x2c00
	s_addc_u32 s5, s5, 0
	global_store_dword v196, v223, s[4:5]
	v_mul_f32_e32 v204, v82, v170
	v_mul_f32_e32 v205, v94, v170
	v_mul_f32_e32 v206, v83, v171
	v_mul_f32_e32 v207, v95, v171
	v_mul_f32_e32 v208, v84, v172
	v_mul_f32_e32 v209, v96, v172
	v_mul_f32_e32 v210, v85, v173
	v_mul_f32_e32 v211, v97, v173
	v_exp_f32_e32 v204, v204
	v_exp_f32_e32 v205, v205
	v_exp_f32_e32 v206, v206
	v_exp_f32_e32 v207, v207
	v_exp_f32_e32 v208, v208
	v_exp_f32_e32 v209, v209
	v_exp_f32_e32 v210, v210
	v_exp_f32_e32 v211, v211
	v_mul_f32_e32 v212, v82, v86
	v_mul_f32_e32 v213, v94, v90
	v_mul_f32_e32 v214, v83, v87
	v_mul_f32_e32 v215, v95, v91
	v_mul_f32_e32 v216, v84, v88
	v_mul_f32_e32 v217, v96, v92
	v_mul_f32_e32 v218, v85, v89
	v_mul_f32_e32 v219, v97, v93
	v_fma_f32 v204, v204, v138, v138
	v_fma_f32 v205, v205, v138, v138
	v_fma_f32 v206, v206, v139, v139
	v_fma_f32 v207, v207, v139, v139
	v_fma_f32 v208, v208, v140, v140
	v_fma_f32 v209, v209, v140, v140
	v_fma_f32 v210, v210, v141, v141
	v_fma_f32 v211, v211, v141, v141
	v_rcp_f32_e32 v204, v204
	v_rcp_f32_e32 v205, v205
	v_rcp_f32_e32 v206, v206
	v_rcp_f32_e32 v207, v207
	v_rcp_f32_e32 v208, v208
	v_rcp_f32_e32 v209, v209
	v_rcp_f32_e32 v210, v210
	v_rcp_f32_e32 v211, v211
	v_mul_f32_e32 v212, v212, v204
	v_mul_f32_e32 v213, v213, v205
	v_mul_f32_e32 v214, v214, v206
	v_mul_f32_e32 v215, v215, v207
	s_add_u32 s4, s24, 0x58000
	s_addc_u32 s5, s25, 0
	v_mul_f32_e32 v216, v216, v208
	v_mul_f32_e32 v217, v217, v209
	v_mul_f32_e32 v218, v218, v210
	v_mul_f32_e32 v219, v219, v211
	v_cvt_pk_bf16_f32 v220, v212, v213
	v_cvt_pk_bf16_f32 v221, v214, v215
	v_cvt_pk_bf16_f32 v222, v216, v217
	v_cvt_pk_bf16_f32 v223, v218, v219
	global_store_dword v196, v220, s[4:5]
	s_add_u32 s4, s4, 0x2c00
	s_addc_u32 s5, s5, 0
	global_store_dword v196, v221, s[4:5]
	s_add_u32 s4, s4, 0x2c00
	s_addc_u32 s5, s5, 0
	global_store_dword v196, v222, s[4:5]
	s_add_u32 s4, s4, 0x2c00
	s_addc_u32 s5, s5, 0
	global_store_dword v196, v223, s[4:5]
	v_mul_f32_e32 v204, v66, v174
	v_mul_f32_e32 v205, v78, v174
	v_mul_f32_e32 v206, v67, v175
	v_mul_f32_e32 v207, v79, v175
	v_mul_f32_e32 v208, v68, v176
	v_mul_f32_e32 v209, v80, v176
	v_mul_f32_e32 v210, v69, v177
	v_mul_f32_e32 v211, v81, v177
	v_exp_f32_e32 v204, v204
	v_exp_f32_e32 v205, v205
	v_exp_f32_e32 v206, v206
	v_exp_f32_e32 v207, v207
	v_exp_f32_e32 v208, v208
	v_exp_f32_e32 v209, v209
	v_exp_f32_e32 v210, v210
	v_exp_f32_e32 v211, v211
	v_mul_f32_e32 v212, v66, v70
	v_mul_f32_e32 v213, v78, v74
	v_mul_f32_e32 v214, v67, v71
	v_mul_f32_e32 v215, v79, v75
	v_mul_f32_e32 v216, v68, v72
	v_mul_f32_e32 v217, v80, v76
	v_mul_f32_e32 v218, v69, v73
	v_mul_f32_e32 v219, v81, v77
	v_fma_f32 v204, v204, v142, v142
	v_fma_f32 v205, v205, v142, v142
	v_fma_f32 v206, v206, v143, v143
	v_fma_f32 v207, v207, v143, v143
	v_fma_f32 v208, v208, v144, v144
	v_fma_f32 v209, v209, v144, v144
	v_fma_f32 v210, v210, v145, v145
	v_fma_f32 v211, v211, v145, v145
	v_rcp_f32_e32 v204, v204
	v_rcp_f32_e32 v205, v205
	v_rcp_f32_e32 v206, v206
	v_rcp_f32_e32 v207, v207
; __device__ __forceinline__ float fdiv(float a, float b) { return a * __builtin_amdgcn_rcpf(b); }
; __device__ __forceinline__ void gemm_tile(const Params& P, const GArgs& ga, const TileDesc& td, int wid_s) {
;     ...
;     static_for<32>([&](auto ic) __attribute__((always_inline)) {
;       EPI_IDX;
;       const float rs = rsv[idx];
;       float g0 = rs * acc[ai][0][m][0][j], u0 = rs * acc[ai][0][m][1][j];
;       float g1 = rs * acc[ai][1][m][0][j], u1 = rs * acc[ai][1][m][1][j];
;       __builtin_nontemporal_store(pack2(fdiv(g0 * u0, 1.f + __expf(-g0)), fdiv(g1 * u1, 1.f + __expf(-g1))), G + (size_t)rl * (FF / 2));
;       if constexpr ((idx & 7) == 7) __builtin_amdgcn_sched_barrier(0);
;     });
	v_rcp_f32_e32 v208, v208
	v_rcp_f32_e32 v209, v209
	v_rcp_f32_e32 v210, v210
	v_rcp_f32_e32 v211, v211
	v_mul_f32_e32 v212, v212, v204
	v_mul_f32_e32 v213, v213, v205
	v_mul_f32_e32 v214, v214, v206
	v_mul_f32_e32 v215, v215, v207
	s_add_u32 s4, s24, 0x84000
	s_addc_u32 s5, s25, 0
	v_mul_f32_e32 v216, v216, v208
	v_mul_f32_e32 v217, v217, v209
	v_mul_f32_e32 v218, v218, v210
	v_mul_f32_e32 v219, v219, v211
	v_cvt_pk_bf16_f32 v220, v212, v213
	v_cvt_pk_bf16_f32 v221, v214, v215
	v_cvt_pk_bf16_f32 v222, v216, v217
	v_cvt_pk_bf16_f32 v223, v218, v219
	global_store_dword v196, v220, s[4:5]
	s_add_u32 s4, s4, 0x2c00
	s_addc_u32 s5, s5, 0
	global_store_dword v196, v221, s[4:5]
	s_add_u32 s4, s4, 0x2c00
	s_addc_u32 s5, s5, 0
	global_store_dword v196, v222, s[4:5]
	s_add_u32 s4, s4, 0x2c00
	s_addc_u32 s5, s5, 0
	global_store_dword v196, v223, s[4:5]
	v_mul_f32_e32 v204, v50, v178
	v_mul_f32_e32 v205, v62, v178
	v_mul_f32_e32 v206, v51, v179
	v_mul_f32_e32 v207, v63, v179
	v_mul_f32_e32 v208, v52, v180
	v_mul_f32_e32 v209, v64, v180
	v_mul_f32_e32 v210, v53, v181
	v_mul_f32_e32 v211, v65, v181
	v_exp_f32_e32 v204, v204
	v_exp_f32_e32 v205, v205
	v_exp_f32_e32 v206, v206
	v_exp_f32_e32 v207, v207
	v_exp_f32_e32 v208, v208
	v_exp_f32_e32 v209, v209
	v_exp_f32_e32 v210, v210
	v_exp_f32_e32 v211, v211
	v_mul_f32_e32 v212, v50, v54
	v_mul_f32_e32 v213, v62, v58
	v_mul_f32_e32 v214, v51, v55
	v_mul_f32_e32 v215, v63, v59
	v_mul_f32_e32 v216, v52, v56
	v_mul_f32_e32 v217, v64, v60
	v_mul_f32_e32 v218, v53, v57
	v_mul_f32_e32 v219, v65, v61
	v_fma_f32 v204, v204, v146, v146
	v_fma_f32 v205, v205, v146, v146
	v_fma_f32 v206, v206, v147, v147
	v_fma_f32 v207, v207, v147, v147
	v_fma_f32 v208, v208, v148, v148
	v_fma_f32 v209, v209, v148, v148
	v_fma_f32 v210, v210, v149, v149
	v_fma_f32 v211, v211, v149, v149
	v_rcp_f32_e32 v204, v204
	v_rcp_f32_e32 v205, v205
	v_rcp_f32_e32 v206, v206
	v_rcp_f32_e32 v207, v207
	v_rcp_f32_e32 v208, v208
	v_rcp_f32_e32 v209, v209
	v_rcp_f32_e32 v210, v210
	v_rcp_f32_e32 v211, v211
	v_mul_f32_e32 v212, v212, v204
	v_mul_f32_e32 v213, v213, v205
	v_mul_f32_e32 v214, v214, v206
	v_mul_f32_e32 v215, v215, v207
	s_add_u32 s4, s24, 0x160000
	s_addc_u32 s5, s25, 0
	v_mul_f32_e32 v216, v216, v208
	v_mul_f32_e32 v217, v217, v209
	v_mul_f32_e32 v218, v218, v210
	v_mul_f32_e32 v219, v219, v211
	v_cvt_pk_bf16_f32 v220, v212, v213
	v_cvt_pk_bf16_f32 v221, v214, v215
	v_cvt_pk_bf16_f32 v222, v216, v217
	v_cvt_pk_bf16_f32 v223, v218, v219
	global_store_dword v196, v220, s[4:5]
	s_add_u32 s4, s4, 0x2c00
	s_addc_u32 s5, s5, 0
	global_store_dword v196, v221, s[4:5]
	s_add_u32 s4, s4, 0x2c00
	s_addc_u32 s5, s5, 0
	global_store_dword v196, v222, s[4:5]
	s_add_u32 s4, s4, 0x2c00
	s_addc_u32 s5, s5, 0
	global_store_dword v196, v223, s[4:5]
	v_mul_f32_e32 v204, v34, v182
	v_mul_f32_e32 v205, v46, v182
	v_mul_f32_e32 v206, v35, v183
	v_mul_f32_e32 v207, v47, v183
	v_mul_f32_e32 v208, v36, v184
	v_mul_f32_e32 v209, v48, v184
	v_mul_f32_e32 v210, v37, v185
	v_mul_f32_e32 v211, v49, v185
	v_exp_f32_e32 v204, v204
	v_exp_f32_e32 v205, v205
	v_exp_f32_e32 v206, v206
	v_exp_f32_e32 v207, v207
	v_exp_f32_e32 v208, v208
	v_exp_f32_e32 v209, v209
	v_exp_f32_e32 v210, v210
	v_exp_f32_e32 v211, v211
	v_mul_f32_e32 v212, v34, v38
	v_mul_f32_e32 v213, v46, v42
	v_mul_f32_e32 v214, v35, v39
	v_mul_f32_e32 v215, v47, v43
	v_mul_f32_e32 v216, v36, v40
	v_mul_f32_e32 v217, v48, v44
	v_mul_f32_e32 v218, v37, v41
	v_mul_f32_e32 v219, v49, v45
	v_fma_f32 v204, v204, v150, v150
	v_fma_f32 v205, v205, v150, v150
	v_fma_f32 v206, v206, v151, v151
	v_fma_f32 v207, v207, v151, v151
	v_fma_f32 v208, v208, v152, v152
	v_fma_f32 v209, v209, v152, v152
	v_fma_f32 v210, v210, v153, v153
	v_fma_f32 v211, v211, v153, v153
	v_rcp_f32_e32 v204, v204
	v_rcp_f32_e32 v205, v205
	v_rcp_f32_e32 v206, v206
	v_rcp_f32_e32 v207, v207
	v_rcp_f32_e32 v208, v208
	v_rcp_f32_e32 v209, v209
	v_rcp_f32_e32 v210, v210
	v_rcp_f32_e32 v211, v211
	v_mul_f32_e32 v212, v212, v204
	v_mul_f32_e32 v213, v213, v205
	v_mul_f32_e32 v214, v214, v206
	v_mul_f32_e32 v215, v215, v207
	s_add_u32 s4, s24, 0x18c000
	s_addc_u32 s5, s25, 0
	v_mul_f32_e32 v216, v216, v208
	v_mul_f32_e32 v217, v217, v209
	v_mul_f32_e32 v218, v218, v210
	v_mul_f32_e32 v219, v219, v211
	v_cvt_pk_bf16_f32 v220, v212, v213
; __device__ __forceinline__ float fdiv(float a, float b) { return a * __builtin_amdgcn_rcpf(b); }
; __device__ __forceinline__ void gemm_tile(const Params& P, const GArgs& ga, const TileDesc& td, int wid_s) {
;     ...
;     static_for<32>([&](auto ic) __attribute__((always_inline)) {
;       EPI_IDX;
;       const float rs = rsv[idx];
;       float g0 = rs * acc[ai][0][m][0][j], u0 = rs * acc[ai][0][m][1][j];
;       float g1 = rs * acc[ai][1][m][0][j], u1 = rs * acc[ai][1][m][1][j];
;       __builtin_nontemporal_store(pack2(fdiv(g0 * u0, 1.f + __expf(-g0)), fdiv(g1 * u1, 1.f + __expf(-g1))), G + (size_t)rl * (FF / 2));
;       if constexpr ((idx & 7) == 7) __builtin_amdgcn_sched_barrier(0);
;     });
	v_cvt_pk_bf16_f32 v221, v214, v215
	v_cvt_pk_bf16_f32 v222, v216, v217
	v_cvt_pk_bf16_f32 v223, v218, v219
	global_store_dword v196, v220, s[4:5]
	s_add_u32 s4, s4, 0x2c00
	s_addc_u32 s5, s5, 0
	global_store_dword v196, v221, s[4:5]
	s_add_u32 s4, s4, 0x2c00
	s_addc_u32 s5, s5, 0
	global_store_dword v196, v222, s[4:5]
	s_add_u32 s4, s4, 0x2c00
	s_addc_u32 s5, s5, 0
	global_store_dword v196, v223, s[4:5]
	v_mul_f32_e32 v204, v18, v186
	v_mul_f32_e32 v205, v30, v186
	v_mul_f32_e32 v206, v19, v187
	v_mul_f32_e32 v207, v31, v187
	v_mul_f32_e32 v208, v20, v188
	v_mul_f32_e32 v209, v32, v188
	v_mul_f32_e32 v210, v21, v189
	v_mul_f32_e32 v211, v33, v189
	v_exp_f32_e32 v204, v204
	v_exp_f32_e32 v205, v205
	v_exp_f32_e32 v206, v206
	v_exp_f32_e32 v207, v207
	v_exp_f32_e32 v208, v208
	v_exp_f32_e32 v209, v209
	v_exp_f32_e32 v210, v210
	v_exp_f32_e32 v211, v211
	v_mul_f32_e32 v212, v18, v22
	v_mul_f32_e32 v213, v30, v26
	v_mul_f32_e32 v214, v19, v23
	v_mul_f32_e32 v215, v31, v27
	v_mul_f32_e32 v216, v20, v24
	v_mul_f32_e32 v217, v32, v28
	v_mul_f32_e32 v218, v21, v25
	v_mul_f32_e32 v219, v33, v29
	v_fma_f32 v204, v204, v154, v154
	v_fma_f32 v205, v205, v154, v154
	v_fma_f32 v206, v206, v155, v155
	v_fma_f32 v207, v207, v155, v155
	v_fma_f32 v208, v208, v156, v156
	v_fma_f32 v209, v209, v156, v156
	v_fma_f32 v210, v210, v157, v157
	v_fma_f32 v211, v211, v157, v157
	v_rcp_f32_e32 v204, v204
	v_rcp_f32_e32 v205, v205
	v_rcp_f32_e32 v206, v206
	v_rcp_f32_e32 v207, v207
	v_rcp_f32_e32 v208, v208
	v_rcp_f32_e32 v209, v209
	v_rcp_f32_e32 v210, v210
	v_rcp_f32_e32 v211, v211
	v_mul_f32_e32 v212, v212, v204
	v_mul_f32_e32 v213, v213, v205
	v_mul_f32_e32 v214, v214, v206
	v_mul_f32_e32 v215, v215, v207
	s_add_u32 s4, s24, 0x1b8000
	s_addc_u32 s5, s25, 0
	v_mul_f32_e32 v216, v216, v208
	v_mul_f32_e32 v217, v217, v209
	v_mul_f32_e32 v218, v218, v210
	v_mul_f32_e32 v219, v219, v211
	v_cvt_pk_bf16_f32 v220, v212, v213
	v_cvt_pk_bf16_f32 v221, v214, v215
	v_cvt_pk_bf16_f32 v222, v216, v217
	v_cvt_pk_bf16_f32 v223, v218, v219
	global_store_dword v196, v220, s[4:5]
	s_add_u32 s4, s4, 0x2c00
	s_addc_u32 s5, s5, 0
	global_store_dword v196, v221, s[4:5]
	s_add_u32 s4, s4, 0x2c00
	s_addc_u32 s5, s5, 0
	global_store_dword v196, v222, s[4:5]
	s_add_u32 s4, s4, 0x2c00
	s_addc_u32 s5, s5, 0
	global_store_dword v196, v223, s[4:5]
	v_mul_f32_e32 v204, v2, v190
	v_mul_f32_e32 v205, v14, v190
	v_mul_f32_e32 v206, v3, v191
	v_mul_f32_e32 v207, v15, v191
	v_mul_f32_e32 v208, v4, v192
	v_mul_f32_e32 v209, v16, v192
	v_mul_f32_e32 v210, v5, v193
	v_mul_f32_e32 v211, v17, v193
	v_exp_f32_e32 v204, v204
	v_exp_f32_e32 v205, v205
	v_exp_f32_e32 v206, v206
	v_exp_f32_e32 v207, v207
	v_exp_f32_e32 v208, v208
	v_exp_f32_e32 v209, v209
	v_exp_f32_e32 v210, v210
	v_exp_f32_e32 v211, v211
	v_mul_f32_e32 v212, v2, v6
	v_mul_f32_e32 v213, v14, v10
	v_mul_f32_e32 v214, v3, v7
	v_mul_f32_e32 v215, v15, v11
	v_mul_f32_e32 v216, v4, v8
	v_mul_f32_e32 v217, v16, v12
	v_mul_f32_e32 v218, v5, v9
	v_mul_f32_e32 v219, v17, v13
	v_fma_f32 v204, v204, v158, v158
	v_fma_f32 v205, v205, v158, v158
	v_fma_f32 v206, v206, v159, v159
	v_fma_f32 v207, v207, v159, v159
	v_fma_f32 v208, v208, v160, v160
	v_fma_f32 v209, v209, v160, v160
	v_fma_f32 v210, v210, v161, v161
	v_fma_f32 v211, v211, v161, v161
	v_rcp_f32_e32 v204, v204
	v_rcp_f32_e32 v205, v205
	v_rcp_f32_e32 v206, v206
	v_rcp_f32_e32 v207, v207
	v_rcp_f32_e32 v208, v208
	v_rcp_f32_e32 v209, v209
	v_rcp_f32_e32 v210, v210
	v_rcp_f32_e32 v211, v211
	v_mul_f32_e32 v212, v212, v204
	v_mul_f32_e32 v213, v213, v205
	v_mul_f32_e32 v214, v214, v206
	v_mul_f32_e32 v215, v215, v207
	s_add_u32 s4, s24, 0x1e4000
	s_addc_u32 s5, s25, 0
	v_mul_f32_e32 v216, v216, v208
	v_mul_f32_e32 v217, v217, v209
	v_mul_f32_e32 v218, v218, v210
	v_mul_f32_e32 v219, v219, v211
	v_cvt_pk_bf16_f32 v220, v212, v213
	v_cvt_pk_bf16_f32 v221, v214, v215
	v_cvt_pk_bf16_f32 v222, v216, v217
	v_cvt_pk_bf16_f32 v223, v218, v219
	global_store_dword v196, v220, s[4:5]
	s_add_u32 s4, s4, 0x2c00
	s_addc_u32 s5, s5, 0
	global_store_dword v196, v221, s[4:5]
	s_add_u32 s4, s4, 0x2c00
	s_addc_u32 s5, s5, 0
	global_store_dword v196, v222, s[4:5]
	s_add_u32 s4, s4, 0x2c00
	s_addc_u32 s5, s5, 0
	global_store_dword v196, v223, s[4:5]
	s_branch .LBB0_290
